# baseline (speedup 1.0000x reference)
; __device__ __forceinline__ unsigned xb_ld(unsigned* p)              { return __hip_atomic_load(p, __ATOMIC_RELAXED, __HIP_MEMORY_SCOPE_AGENT); }
; __device__ __forceinline__ unsigned xb_add(unsigned* p, unsigned v) { return __hip_atomic_fetch_add(p, v, __ATOMIC_RELAXED, __HIP_MEMORY_SCOPE_AGENT); }
; #define XB_SPIN(cond, bar) do { unsigned _sp = 0; while (cond) { __builtin_amdgcn_s_sleep(1); \
;     if ((++_sp & 255u) == 0u) { if (xb_ld(&(bar)[XB_TMO])) break; if (_sp > XB_SPIN_CAP) { atomicAdd(&(bar)[XB_TMO], 1u); break; } } } } while (0)
; __device__ __forceinline__ void xcd_barrier(unsigned* bar, volatile LAS unsigned* st) {
;     ...
;         const unsigned old = xb_add(&bar[XB_XSUB(x)], 1u);
;         const unsigned gen = old / nloc;
;         if (old + 1u == (gen + 1u) * nloc) {
;             __builtin_amdgcn_fence(__ATOMIC_RELEASE, "agent");
;             asm volatile("s_waitcnt vmcnt(0)" ::: "memory");
;             const unsigned og = xb_add(&bar[XB_TOP], 1u);
;             const unsigned tg = og / nx;
;             if (og + 1u == (tg + 1u) * nx) xb_add(&bar[XB_TOPGEN], 1u);
;             else XB_SPIN(xb_ld(&bar[XB_TOPGEN]) == tg, bar);
;             xb_add(&bar[XB_XGEN(x)], 1u);
;             __builtin_amdgcn_fence(__ATOMIC_ACQUIRE, "agent");
;             asm volatile("s_waitcnt vmcnt(0)" ::: "memory");
;         } else {
;             XB_SPIN(xb_ld(&bar[XB_XGEN(x)]) == gen, bar);
;             __builtin_amdgcn_fence(__ATOMIC_ACQUIRE, "agent");
;             asm volatile("s_waitcnt vmcnt(0)" ::: "memory");
;         }
.LBB0_328:
	s_or_b64 exec, exec, s[12:13]
	v_cvt_f32_u32_e32 v5, v3
	s_waitcnt vmcnt(1)
	v_readfirstlane_b32 s10, v4
	s_mov_b32 s99, s98
	v_sub_u32_e32 v4, 0, v3
	v_rcp_iflag_f32_e32 v5, v5
	v_add_u32_e32 v6, s10, v2
	v_mul_f32_e32 v5, 0x4f7ffffe, v5
	v_cvt_u32_f32_e32 v5, v5
	v_mul_lo_u32 v2, v4, v5
	v_mul_hi_u32 v2, v5, v2
	v_add_u32_e32 v2, v5, v2
	v_mul_hi_u32 v2, v6, v2
	v_mul_lo_u32 v4, v2, v3
	v_sub_u32_e32 v4, v6, v4
	v_add_u32_e32 v5, 1, v2
	v_sub_u32_e32 v7, v4, v3
	v_cmp_ge_u32_e32 vcc, v4, v3
	s_nop 1
	v_cndmask_b32_e32 v2, v2, v5, vcc
	v_cndmask_b32_e32 v4, v4, v7, vcc
	v_add_u32_e32 v5, 1, v2
	v_cmp_ge_u32_e32 vcc, v4, v3
	v_add_u32_e32 v4, 1, v6
	s_nop 0
	v_cndmask_b32_e32 v2, v2, v5, vcc
	v_mul_lo_u32 v5, v3, v2
	v_add_u32_e32 v3, v5, v3
	v_cmp_ne_u32_e32 vcc, v4, v3
	s_and_saveexec_b64 s[10:11], vcc
	s_xor_b64 s[10:11], exec, s[10:11]
	s_cbranch_execz .LBB0_342
	s_waitcnt lgkmcnt(0)
	v_mov_b32_e32 v0, 0x2000
	s_lshl_b32 s99, s99, 12
	v_subrev_u32_e32 v0, s99, v0
	global_load_dword v0, v0, s[8:9] offset:1024 sc1
	s_add_u32 s26, s8, 0x2400
	s_addc_u32 s27, s9, 0
	s_sub_u32 s26, s26, s99
	s_subb_u32 s27, s27, 0
	s_cmp_lg_u32 s99, 0
	s_cbranch_scc0 .Lxs_glob_0
	v_add_u32_e32 v2, -1, v3
.Lxs_glob_0:
	s_waitcnt vmcnt(0)
	v_cmp_le_u32_e32 vcc, v0, v2
	s_and_saveexec_b64 s[12:13], vcc
	s_cbranch_execz .LBB0_341
	s_add_u32 s16, s6, 0x12b90200
	s_addc_u32 s17, s7, 0
	s_mov_b32 s20, 1
	s_mov_b64 s[28:29], 0
	s_branch .LBB0_332

; __device__ __forceinline__ unsigned xb_ld(unsigned* p)              { return __hip_atomic_load(p, __ATOMIC_RELAXED, __HIP_MEMORY_SCOPE_AGENT); }
; #define XB_SPIN(cond, bar) do { unsigned _sp = 0; while (cond) { __builtin_amdgcn_s_sleep(1); \
;     if ((++_sp & 255u) == 0u) { if (xb_ld(&(bar)[XB_TMO])) break; if (_sp > XB_SPIN_CAP) { atomicAdd(&(bar)[XB_TMO], 1u); break; } } } } while (0)
; __device__ __forceinline__ void xcd_barrier(unsigned* bar, volatile LAS unsigned* st) {
;     ...
;         } else {
;             XB_SPIN(xb_ld(&bar[XB_XGEN(x)]) == gen, bar);
;             __builtin_amdgcn_fence(__ATOMIC_ACQUIRE, "agent");
;             asm volatile("s_waitcnt vmcnt(0)" ::: "memory");
.LBB0_334:
	global_load_dword v0, v1, s[26:27] sc1
	s_add_i32 s20, s20, 1
	s_mov_b64 s[44:45], -1
	s_waitcnt vmcnt(0)
	v_cmp_gt_u32_e32 vcc, v0, v2
	s_orn2_b64 s[42:43], vcc, exec
	s_branch .LBB0_331

; __device__ __forceinline__ unsigned xb_ld(unsigned* p)              { return __hip_atomic_load(p, __ATOMIC_RELAXED, __HIP_MEMORY_SCOPE_AGENT); }
; __device__ __forceinline__ unsigned xb_add(unsigned* p, unsigned v) { return __hip_atomic_fetch_add(p, v, __ATOMIC_RELAXED, __HIP_MEMORY_SCOPE_AGENT); }
; #define XB_SPIN(cond, bar) do { unsigned _sp = 0; while (cond) { __builtin_amdgcn_s_sleep(1); \
;     if ((++_sp & 255u) == 0u) { if (xb_ld(&(bar)[XB_TMO])) break; if (_sp > XB_SPIN_CAP) { atomicAdd(&(bar)[XB_TMO], 1u); break; } } } } while (0)
; __device__ __forceinline__ void xcd_barrier(unsigned* bar, volatile LAS unsigned* st) {
;     ...
;         const unsigned old = xb_add(&bar[XB_XSUB(x)], 1u);
;         const unsigned gen = old / nloc;
;         if (old + 1u == (gen + 1u) * nloc) {
;             __builtin_amdgcn_fence(__ATOMIC_RELEASE, "agent");
;             asm volatile("s_waitcnt vmcnt(0)" ::: "memory");
;             const unsigned og = xb_add(&bar[XB_TOP], 1u);
;             const unsigned tg = og / nx;
;             if (og + 1u == (tg + 1u) * nx) xb_add(&bar[XB_TOPGEN], 1u);
;             else XB_SPIN(xb_ld(&bar[XB_TOPGEN]) == tg, bar);
;             xb_add(&bar[XB_XGEN(x)], 1u);
;             __builtin_amdgcn_fence(__ATOMIC_ACQUIRE, "agent");
;             asm volatile("s_waitcnt vmcnt(0)" ::: "memory");
;         } else {
;             XB_SPIN(xb_ld(&bar[XB_XGEN(x)]) == gen, bar);
;             __builtin_amdgcn_fence(__ATOMIC_ACQUIRE, "agent");
;             asm volatile("s_waitcnt vmcnt(0)" ::: "memory");
;         }
.LBB0_421:
	s_or_b64 exec, exec, s[16:17]
	v_cvt_f32_u32_e32 v5, v3
	s_waitcnt vmcnt(1)
	v_readfirstlane_b32 s12, v4
	s_and_b32 s99, s98, s92
	v_sub_u32_e32 v4, 0, v3
	v_rcp_iflag_f32_e32 v5, v5
	v_add_u32_e32 v6, s12, v0
	v_mul_f32_e32 v5, 0x4f7ffffe, v5
	v_cvt_u32_f32_e32 v5, v5
	v_mul_lo_u32 v0, v4, v5
	v_mul_hi_u32 v0, v5, v0
	v_add_u32_e32 v0, v5, v0
	v_mul_hi_u32 v0, v6, v0
	v_mul_lo_u32 v4, v0, v3
	v_sub_u32_e32 v4, v6, v4
	v_add_u32_e32 v5, 1, v0
	v_cmp_ge_u32_e32 vcc, v4, v3
	s_nop 1
	v_cndmask_b32_e32 v0, v0, v5, vcc
	v_sub_u32_e32 v5, v4, v3
	v_cndmask_b32_e32 v4, v4, v5, vcc
	v_add_u32_e32 v5, 1, v0
	v_cmp_ge_u32_e32 vcc, v4, v3
	v_add_u32_e32 v4, 1, v6
	s_nop 0
	v_cndmask_b32_e32 v0, v0, v5, vcc
	v_mul_lo_u32 v5, v3, v0
	v_add_u32_e32 v3, v5, v3
	v_cmp_ne_u32_e32 vcc, v4, v3
	s_and_saveexec_b64 s[12:13], vcc
	s_xor_b64 s[16:17], exec, s[12:13]
	s_cbranch_execz .LBB0_435
	s_waitcnt lgkmcnt(0)
	v_mov_b32_e32 v2, 0x2000
	s_lshl_b32 s99, s99, 12
	v_subrev_u32_e32 v2, s99, v2
	global_load_dword v2, v2, s[10:11] offset:1024 sc1
	s_add_u32 s28, s10, 0x2400
	s_addc_u32 s29, s11, 0
	s_sub_u32 s28, s28, s99
	s_subb_u32 s29, s29, 0
	s_cmp_lg_u32 s99, 0
	s_cbranch_scc0 .Lxs_glob_1
	v_add_u32_e32 v0, -1, v3
.Lxs_glob_1:
	s_waitcnt vmcnt(0)
	v_cmp_le_u32_e32 vcc, v2, v0
	s_and_saveexec_b64 s[12:13], vcc
	s_cbranch_execz .LBB0_434
	s_add_u32 s26, s8, 0x12b90200
	s_addc_u32 s27, s9, 0
	s_mov_b32 s20, 1
	s_mov_b64 s[30:31], 0
	s_branch .LBB0_425

; __device__ __forceinline__ unsigned xb_ld(unsigned* p)              { return __hip_atomic_load(p, __ATOMIC_RELAXED, __HIP_MEMORY_SCOPE_AGENT); }
; #define XB_SPIN(cond, bar) do { unsigned _sp = 0; while (cond) { __builtin_amdgcn_s_sleep(1); \
;     if ((++_sp & 255u) == 0u) { if (xb_ld(&(bar)[XB_TMO])) break; if (_sp > XB_SPIN_CAP) { atomicAdd(&(bar)[XB_TMO], 1u); break; } } } } while (0)
; __device__ __forceinline__ void xcd_barrier(unsigned* bar, volatile LAS unsigned* st) {
;     ...
;         } else {
;             XB_SPIN(xb_ld(&bar[XB_XGEN(x)]) == gen, bar);
;             __builtin_amdgcn_fence(__ATOMIC_ACQUIRE, "agent");
;             asm volatile("s_waitcnt vmcnt(0)" ::: "memory");
.LBB0_427:
	global_load_dword v2, v1, s[28:29] sc1
	s_add_i32 s20, s20, 1
	s_mov_b64 s[46:47], -1
	s_waitcnt vmcnt(0)
	v_cmp_gt_u32_e32 vcc, v2, v0
	s_orn2_b64 s[44:45], vcc, exec
	s_branch .LBB0_424

; __device__ __forceinline__ unsigned xb_ld(unsigned* p)              { return __hip_atomic_load(p, __ATOMIC_RELAXED, __HIP_MEMORY_SCOPE_AGENT); }
; __device__ __forceinline__ unsigned xb_add(unsigned* p, unsigned v) { return __hip_atomic_fetch_add(p, v, __ATOMIC_RELAXED, __HIP_MEMORY_SCOPE_AGENT); }
; #define XB_SPIN(cond, bar) do { unsigned _sp = 0; while (cond) { __builtin_amdgcn_s_sleep(1); \
;     if ((++_sp & 255u) == 0u) { if (xb_ld(&(bar)[XB_TMO])) break; if (_sp > XB_SPIN_CAP) { atomicAdd(&(bar)[XB_TMO], 1u); break; } } } } while (0)
; __device__ __forceinline__ void xcd_barrier(unsigned* bar, volatile LAS unsigned* st) {
;     ...
;         const unsigned old = xb_add(&bar[XB_XSUB(x)], 1u);
;         const unsigned gen = old / nloc;
;         if (old + 1u == (gen + 1u) * nloc) {
;             __builtin_amdgcn_fence(__ATOMIC_RELEASE, "agent");
;             asm volatile("s_waitcnt vmcnt(0)" ::: "memory");
;             const unsigned og = xb_add(&bar[XB_TOP], 1u);
;             const unsigned tg = og / nx;
;             if (og + 1u == (tg + 1u) * nx) xb_add(&bar[XB_TOPGEN], 1u);
;             else XB_SPIN(xb_ld(&bar[XB_TOPGEN]) == tg, bar);
;             xb_add(&bar[XB_XGEN(x)], 1u);
;             __builtin_amdgcn_fence(__ATOMIC_ACQUIRE, "agent");
;             asm volatile("s_waitcnt vmcnt(0)" ::: "memory");
;         } else {
;             XB_SPIN(xb_ld(&bar[XB_XGEN(x)]) == gen, bar);
;             __builtin_amdgcn_fence(__ATOMIC_ACQUIRE, "agent");
;             asm volatile("s_waitcnt vmcnt(0)" ::: "memory");
;         }
.LBB0_520:
	s_or_b64 exec, exec, s[16:17]
	v_cvt_f32_u32_e32 v5, v3
	s_waitcnt vmcnt(1)
	v_readfirstlane_b32 s12, v4
	s_cmp_lg_u32 s82, 4
	s_cselect_b32 s99, s98, 0
	v_sub_u32_e32 v4, 0, v3
	v_rcp_iflag_f32_e32 v5, v5
	v_add_u32_e32 v6, s12, v0
	v_mul_f32_e32 v5, 0x4f7ffffe, v5
	v_cvt_u32_f32_e32 v5, v5
	v_mul_lo_u32 v0, v4, v5
	v_mul_hi_u32 v0, v5, v0
	v_add_u32_e32 v0, v5, v0
	v_mul_hi_u32 v0, v6, v0
	v_mul_lo_u32 v4, v0, v3
	v_sub_u32_e32 v4, v6, v4
	v_add_u32_e32 v5, 1, v0
	v_cmp_ge_u32_e32 vcc, v4, v3
	s_nop 1
	v_cndmask_b32_e32 v0, v0, v5, vcc
	v_sub_u32_e32 v5, v4, v3
	v_cndmask_b32_e32 v4, v4, v5, vcc
	v_add_u32_e32 v5, 1, v0
	v_cmp_ge_u32_e32 vcc, v4, v3
	v_add_u32_e32 v4, 1, v6
	s_nop 0
	v_cndmask_b32_e32 v0, v0, v5, vcc
	v_mul_lo_u32 v5, v3, v0
	v_add_u32_e32 v3, v5, v3
	v_cmp_ne_u32_e32 vcc, v4, v3
	s_and_saveexec_b64 s[12:13], vcc
	s_xor_b64 s[16:17], exec, s[12:13]
	s_cbranch_execz .LBB0_534
	s_waitcnt lgkmcnt(0)
	v_mov_b32_e32 v2, 0x2000
	s_lshl_b32 s99, s99, 12
	v_subrev_u32_e32 v2, s99, v2
	global_load_dword v2, v2, s[10:11] offset:1024 sc1
	s_add_u32 s28, s10, 0x2400
	s_addc_u32 s29, s11, 0
	s_sub_u32 s28, s28, s99
	s_subb_u32 s29, s29, 0
	s_cmp_lg_u32 s99, 0
	s_cbranch_scc0 .Lxs_glob_2
	v_add_u32_e32 v0, -1, v3

; __device__ __forceinline__ unsigned xb_ld(unsigned* p)              { return __hip_atomic_load(p, __ATOMIC_RELAXED, __HIP_MEMORY_SCOPE_AGENT); }
; __device__ __forceinline__ unsigned xb_add(unsigned* p, unsigned v) { return __hip_atomic_fetch_add(p, v, __ATOMIC_RELAXED, __HIP_MEMORY_SCOPE_AGENT); }
; #define XB_SPIN(cond, bar) do { unsigned _sp = 0; while (cond) { __builtin_amdgcn_s_sleep(1); \
;     if ((++_sp & 255u) == 0u) { if (xb_ld(&(bar)[XB_TMO])) break; if (_sp > XB_SPIN_CAP) { atomicAdd(&(bar)[XB_TMO], 1u); break; } } } } while (0)
; __device__ __forceinline__ void xcd_barrier(unsigned* bar, volatile LAS unsigned* st) {
;     ...
;         const unsigned old = xb_add(&bar[XB_XSUB(x)], 1u);
;         const unsigned gen = old / nloc;
;         if (old + 1u == (gen + 1u) * nloc) {
;             __builtin_amdgcn_fence(__ATOMIC_RELEASE, "agent");
;             asm volatile("s_waitcnt vmcnt(0)" ::: "memory");
;             const unsigned og = xb_add(&bar[XB_TOP], 1u);
;             const unsigned tg = og / nx;
;             if (og + 1u == (tg + 1u) * nx) xb_add(&bar[XB_TOPGEN], 1u);
;             else XB_SPIN(xb_ld(&bar[XB_TOPGEN]) == tg, bar);
;             xb_add(&bar[XB_XGEN(x)], 1u);
;             __builtin_amdgcn_fence(__ATOMIC_ACQUIRE, "agent");
;             asm volatile("s_waitcnt vmcnt(0)" ::: "memory");
;         } else {
;             XB_SPIN(xb_ld(&bar[XB_XGEN(x)]) == gen, bar);
;             __builtin_amdgcn_fence(__ATOMIC_ACQUIRE, "agent");
;             asm volatile("s_waitcnt vmcnt(0)" ::: "memory");
;         }
.LBB0_604:
	s_or_b64 exec, exec, s[16:17]
	v_cvt_f32_u32_e32 v5, v3
	s_waitcnt vmcnt(1)
	v_readfirstlane_b32 s12, v4
	s_mov_b32 s99, s98
	v_sub_u32_e32 v4, 0, v3
	v_rcp_iflag_f32_e32 v5, v5
	v_add_u32_e32 v6, s12, v0
	v_mul_f32_e32 v5, 0x4f7ffffe, v5
	v_cvt_u32_f32_e32 v5, v5
	v_mul_lo_u32 v0, v4, v5
	v_mul_hi_u32 v0, v5, v0
	v_add_u32_e32 v0, v5, v0
	v_mul_hi_u32 v0, v6, v0
	v_mul_lo_u32 v4, v0, v3
	v_sub_u32_e32 v4, v6, v4
	v_add_u32_e32 v5, 1, v0
	v_cmp_ge_u32_e32 vcc, v4, v3
	s_nop 1
	v_cndmask_b32_e32 v0, v0, v5, vcc
	v_sub_u32_e32 v5, v4, v3
	v_cndmask_b32_e32 v4, v4, v5, vcc
	v_add_u32_e32 v5, 1, v0
	v_cmp_ge_u32_e32 vcc, v4, v3
	v_add_u32_e32 v4, 1, v6
	s_nop 0
	v_cndmask_b32_e32 v0, v0, v5, vcc
	v_mul_lo_u32 v5, v3, v0
	v_add_u32_e32 v3, v5, v3
	v_cmp_ne_u32_e32 vcc, v4, v3
	s_and_saveexec_b64 s[12:13], vcc
	s_xor_b64 s[16:17], exec, s[12:13]
	s_cbranch_execz .LBB0_618
	s_waitcnt lgkmcnt(0)
	v_mov_b32_e32 v2, 0x2000
	s_lshl_b32 s99, s99, 12
	v_subrev_u32_e32 v2, s99, v2
	global_load_dword v2, v2, s[10:11] offset:1024 sc1
	s_add_u32 s28, s10, 0x2400
	s_addc_u32 s29, s11, 0
	s_sub_u32 s28, s28, s99
	s_subb_u32 s29, s29, 0
	s_cmp_lg_u32 s99, 0
	s_cbranch_scc0 .Lxs_glob_3
	v_add_u32_e32 v0, -1, v3

; __device__ __forceinline__ unsigned xb_ld(unsigned* p)              { return __hip_atomic_load(p, __ATOMIC_RELAXED, __HIP_MEMORY_SCOPE_AGENT); }
; __device__ __forceinline__ unsigned xb_add(unsigned* p, unsigned v) { return __hip_atomic_fetch_add(p, v, __ATOMIC_RELAXED, __HIP_MEMORY_SCOPE_AGENT); }
; #define XB_SPIN(cond, bar) do { unsigned _sp = 0; while (cond) { __builtin_amdgcn_s_sleep(1); \
;     if ((++_sp & 255u) == 0u) { if (xb_ld(&(bar)[XB_TMO])) break; if (_sp > XB_SPIN_CAP) { atomicAdd(&(bar)[XB_TMO], 1u); break; } } } } while (0)
; __device__ __forceinline__ void xcd_barrier(unsigned* bar, volatile LAS unsigned* st) {
;     ...
;         const unsigned old = xb_add(&bar[XB_XSUB(x)], 1u);
;         const unsigned gen = old / nloc;
;         if (old + 1u == (gen + 1u) * nloc) {
;             __builtin_amdgcn_fence(__ATOMIC_RELEASE, "agent");
;             asm volatile("s_waitcnt vmcnt(0)" ::: "memory");
;             const unsigned og = xb_add(&bar[XB_TOP], 1u);
;             const unsigned tg = og / nx;
;             if (og + 1u == (tg + 1u) * nx) xb_add(&bar[XB_TOPGEN], 1u);
;             else XB_SPIN(xb_ld(&bar[XB_TOPGEN]) == tg, bar);
;             xb_add(&bar[XB_XGEN(x)], 1u);
;             __builtin_amdgcn_fence(__ATOMIC_ACQUIRE, "agent");
;             asm volatile("s_waitcnt vmcnt(0)" ::: "memory");
;         } else {
;             XB_SPIN(xb_ld(&bar[XB_XGEN(x)]) == gen, bar);
;             __builtin_amdgcn_fence(__ATOMIC_ACQUIRE, "agent");
;             asm volatile("s_waitcnt vmcnt(0)" ::: "memory");
;         }
.LBB0_906:
	s_or_b64 exec, exec, s[12:13]
	v_cvt_f32_u32_e32 v5, v3
	s_waitcnt vmcnt(1)
	v_readfirstlane_b32 s10, v4
	v_sub_u32_e32 v4, 0, v3
	v_rcp_iflag_f32_e32 v5, v5
	v_add_u32_e32 v6, s10, v0
	v_mul_f32_e32 v5, 0x4f7ffffe, v5
	v_cvt_u32_f32_e32 v5, v5
	v_mul_lo_u32 v0, v4, v5
	v_mul_hi_u32 v0, v5, v0
	v_add_u32_e32 v0, v5, v0
	v_mul_hi_u32 v0, v6, v0
	v_mul_lo_u32 v4, v0, v3
	v_sub_u32_e32 v4, v6, v4
	v_add_u32_e32 v5, 1, v0
	v_cmp_ge_u32_e32 vcc, v4, v3
	s_nop 1
	v_cndmask_b32_e32 v0, v0, v5, vcc
	v_sub_u32_e32 v5, v4, v3
	v_cndmask_b32_e32 v4, v4, v5, vcc
	v_add_u32_e32 v5, 1, v0
	v_cmp_ge_u32_e32 vcc, v4, v3
	v_add_u32_e32 v4, 1, v6
	s_nop 0
	v_cndmask_b32_e32 v0, v0, v5, vcc
	v_mul_lo_u32 v5, v3, v0
	v_add_u32_e32 v3, v5, v3
	v_cmp_ne_u32_e32 vcc, v4, v3
	s_and_saveexec_b64 s[10:11], vcc
	s_xor_b64 s[10:11], exec, s[10:11]
	s_cbranch_execz .LBB0_920
	s_waitcnt lgkmcnt(0)
	v_mov_b32_e32 v2, 0x2000
	global_load_dword v2, v2, s[8:9] offset:1024 sc1
	s_add_u32 s26, s8, 0x2400
	s_addc_u32 s27, s9, 0
	s_waitcnt vmcnt(0)
	v_cmp_le_u32_e32 vcc, v2, v0
	s_and_saveexec_b64 s[12:13], vcc
	s_cbranch_execz .LBB0_919
	s_add_u32 s16, s6, 0x12b90200
	s_addc_u32 s17, s7, 0
	s_mov_b32 s20, 1
	s_mov_b64 s[28:29], 0
	s_branch .LBB0_910

; __device__ __forceinline__ unsigned xb_ld(unsigned* p)              { return __hip_atomic_load(p, __ATOMIC_RELAXED, __HIP_MEMORY_SCOPE_AGENT); }
; #define XB_SPIN(cond, bar) do { unsigned _sp = 0; while (cond) { __builtin_amdgcn_s_sleep(1); \
;     if ((++_sp & 255u) == 0u) { if (xb_ld(&(bar)[XB_TMO])) break; if (_sp > XB_SPIN_CAP) { atomicAdd(&(bar)[XB_TMO], 1u); break; } } } } while (0)
; __device__ __forceinline__ void xcd_barrier(unsigned* bar, volatile LAS unsigned* st) {
;     ...
;         } else {
;             XB_SPIN(xb_ld(&bar[XB_XGEN(x)]) == gen, bar);
;             __builtin_amdgcn_fence(__ATOMIC_ACQUIRE, "agent");
;             asm volatile("s_waitcnt vmcnt(0)" ::: "memory");
.LBB0_912:
	global_load_dword v2, v1, s[26:27] sc1
	s_add_i32 s20, s20, 1
	s_mov_b64 s[44:45], -1
	s_waitcnt vmcnt(0)
	v_cmp_gt_u32_e32 vcc, v2, v0
	s_orn2_b64 s[42:43], vcc, exec
	s_branch .LBB0_909
